# mode-3 K-loop balanced like mode 0: next-tile pointer selection and DMA bases computed in the light segments (one iteration ahead), heavy segments keep only M0 writes
# speedup vs baseline: 1.0159x; 1.0028x over previous
; #define PG8_STAGE(bufoff, gbase, voff) do { _Pragma("unroll") for (int _i = 0; _i < 2; ++_i) \
;         __builtin_amdgcn_global_load_lds((const unsigned*)((const char*)(gbase) + (voff)[_i]), (LAS unsigned*)(lds + (bufoff) + ldsw + _i * 8192), 16, 0, 0); } while (0)
; #define PG8_LDA(dst, b, h) do { _Pragma("unroll") for (int m = 0; m < 4; ++m) _Pragma("unroll") for (int k = 0; k < 2; ++k) dst[m][k] = *(const LAS bf16x8*)(lds + PG8_SA(b, h) + aoff + m * 2048 + k * 1024); } while (0)
; #define PG8_LDB(dst, b, h) do { _Pragma("unroll") for (int n = 0; n < 2; ++n) _Pragma("unroll") for (int k = 0; k < 2; ++k) dst[n][k] = *(const LAS bf16x8*)(lds + PG8_SB(b, h) + boff + n * 2048 + k * 1024); } while (0)
; #define PG8_WAIT_L(n) asm volatile("s_waitcnt lgkmcnt(" #n ")" ::: "memory")
; #define PG8_BAR __builtin_amdgcn_s_barrier()
; #define PG8_SCHED __builtin_amdgcn_sched_barrier(0)
; template <int MODE, class EpiT, class Sched>
; __device__ __forceinline__ void gemm_phase(LAS unsigned char* lds, const Gemm g, const Sched& S, const EpiT& E) {
;     ...
;     f32x4 acc[2][2][4][2];
; #pragma unroll
;     for (int a = 0; a < 2; ++a)
; #pragma unroll
;         for (int b = 0; b < 2; ++b)
; #pragma unroll
;             for (int m = 0; m < 4; ++m)
; #pragma unroll
;                 for (int n = 0; n < 2; ++n) acc[a][b][m][n] = (f32x4){0.f, 0.f, 0.f, 0.f};
;     ...
;         const bool has_next = S.next(ui + 1, nxt);
;         const char* nA = has_next ? (const char*)g.A + (size_t)nxt.pm * tstep : cA; const char* nB = has_next ? (const char*)g.Bt + (size_t)nxt.pn * tstep : cB;
;         for (int t = 0; t < nt; t += 2) {
;             const bool last = (t == nt - 2);
;             const char* a1 = cA + (size_t)(t + 1) * kstep;
;             const char* a2 = last ? nA : cA + (size_t)(t + 2) * kstep; const char* b2 = last ? nB : cB + (size_t)(t + 2) * kstep;
;             const char* a3 = a2 + kstep; const char* b3 = b2 + kstep;
;             PG8_LDB(B0, 0, 0); PG8_SCHED; PG8_LDA(At, 0, 0); PG8_STAGE(PG8_SA(1, 1), a1 + hstep, voffA);
;             PG8_WAIT_L(8); PG8_BAR; PG8_WAIT_L(0); PG8_MMA(0, 0, At, B0); PG8_BAR; PG8_SCHED;
;             PG8_LDB(B1, 0, 1); PG8_STAGE(PG8_SB(0, 0), b2, voffB);
;             PG8_BAR; PG8_WAIT_L(0); PG8_MMA(0, 1, At, B1); PG8_BAR;
.LBB0_194:
	s_add_u32 s4, s4, 0x80
	s_addc_u32 s5, s5, 0
	s_add_u32 s89, s52, 0x100
	v_mov_b32_e32 v2, 0
	s_addc_u32 s90, s53, 0
	s_mov_b32 s44, 0
	s_add_u32 s100, s4, 0x80
	s_addc_u32 s101, s5, 0
	s_cmp_eq_u32 s75, 0
	s_cselect_b32 s44, s68, s100
	s_cselect_b32 s45, s69, s101
	s_cselect_b32 s53, s47, s90
	s_cselect_b32 s52, s46, s89
	s_add_u32 s98, s52, 0x80
	s_addc_u32 s99, s53, 0
	s_add_u32 s100, s4, s38
	s_addc_u32 s101, s5, 0
	s_mov_b32 vcc_lo, 0
	v_mov_b32_e32 v3, v2
	v_mov_b32_e32 v4, v2
	v_mov_b32_e32 v5, v2
	v_mov_b32_e32 v6, v2
	v_mov_b32_e32 v7, v2
	v_mov_b32_e32 v8, v2
	v_mov_b32_e32 v9, v2
	v_mov_b32_e32 v18, v2
	v_mov_b32_e32 v19, v2
	v_mov_b32_e32 v20, v2
	v_mov_b32_e32 v21, v2
	v_mov_b32_e32 v22, v2
	v_mov_b32_e32 v23, v2
	v_mov_b32_e32 v24, v2
	v_mov_b32_e32 v25, v2
	v_mov_b32_e32 v34, v2
	v_mov_b32_e32 v35, v2
	v_mov_b32_e32 v36, v2
	v_mov_b32_e32 v37, v2
	v_mov_b32_e32 v38, v2
	v_mov_b32_e32 v39, v2
	v_mov_b32_e32 v40, v2
	v_mov_b32_e32 v41, v2
	v_mov_b32_e32 v50, v2
	v_mov_b32_e32 v51, v2
	v_mov_b32_e32 v52, v2
	v_mov_b32_e32 v53, v2
	v_mov_b32_e32 v54, v2
	v_mov_b32_e32 v55, v2
	v_mov_b32_e32 v56, v2
	v_mov_b32_e32 v57, v2
	v_mov_b32_e32 v10, v2
	v_mov_b32_e32 v11, v2
	v_mov_b32_e32 v12, v2
	v_mov_b32_e32 v13, v2
	v_mov_b32_e32 v14, v2
	v_mov_b32_e32 v15, v2
	v_mov_b32_e32 v16, v2
	v_mov_b32_e32 v17, v2
	v_mov_b32_e32 v26, v2
	v_mov_b32_e32 v27, v2
	v_mov_b32_e32 v28, v2
	v_mov_b32_e32 v29, v2
	v_mov_b32_e32 v30, v2
	v_mov_b32_e32 v31, v2
	v_mov_b32_e32 v32, v2
	v_mov_b32_e32 v33, v2
	v_mov_b32_e32 v42, v2
	v_mov_b32_e32 v43, v2
	v_mov_b32_e32 v44, v2
	v_mov_b32_e32 v45, v2
	v_mov_b32_e32 v46, v2
	v_mov_b32_e32 v47, v2
	v_mov_b32_e32 v48, v2
	v_mov_b32_e32 v49, v2
	v_mov_b32_e32 v66, v2
	v_mov_b32_e32 v67, v2
	v_mov_b32_e32 v68, v2
	v_mov_b32_e32 v69, v2
	v_mov_b32_e32 v78, v2
	v_mov_b32_e32 v79, v2
	v_mov_b32_e32 v80, v2
	v_mov_b32_e32 v81, v2
	v_mov_b32_e32 v82, v2
	v_mov_b32_e32 v83, v2
	v_mov_b32_e32 v84, v2
	v_mov_b32_e32 v85, v2
	v_mov_b32_e32 v86, v2
	v_mov_b32_e32 v87, v2
	v_mov_b32_e32 v88, v2
	v_mov_b32_e32 v89, v2
	v_mov_b32_e32 v98, v2
	v_mov_b32_e32 v99, v2
	v_mov_b32_e32 v100, v2
	v_mov_b32_e32 v101, v2
	v_mov_b32_e32 v102, v2
	v_mov_b32_e32 v103, v2
	v_mov_b32_e32 v104, v2
	v_mov_b32_e32 v105, v2
	v_mov_b32_e32 v114, v2
	v_mov_b32_e32 v115, v2
	v_mov_b32_e32 v116, v2
	v_mov_b32_e32 v117, v2
	v_mov_b32_e32 v118, v2
	v_mov_b32_e32 v119, v2
	v_mov_b32_e32 v120, v2
	v_mov_b32_e32 v121, v2
	v_mov_b32_e32 v130, v2
	v_mov_b32_e32 v131, v2
	v_mov_b32_e32 v132, v2
	v_mov_b32_e32 v133, v2
	v_mov_b32_e32 v134, v2
	v_mov_b32_e32 v135, v2
	v_mov_b32_e32 v136, v2
	v_mov_b32_e32 v137, v2
	v_mov_b32_e32 v90, v2
	v_mov_b32_e32 v91, v2
	v_mov_b32_e32 v92, v2
	v_mov_b32_e32 v93, v2
	v_mov_b32_e32 v94, v2
	v_mov_b32_e32 v95, v2
	v_mov_b32_e32 v96, v2
	v_mov_b32_e32 v97, v2
	v_mov_b32_e32 v106, v2
	v_mov_b32_e32 v107, v2
	v_mov_b32_e32 v108, v2
	v_mov_b32_e32 v109, v2
	v_mov_b32_e32 v110, v2
	v_mov_b32_e32 v111, v2
	v_mov_b32_e32 v112, v2
	v_mov_b32_e32 v113, v2
	v_mov_b32_e32 v122, v2
	v_mov_b32_e32 v123, v2
	v_mov_b32_e32 v124, v2
	v_mov_b32_e32 v125, v2
	v_mov_b32_e32 v126, v2
	v_mov_b32_e32 v127, v2
	v_mov_b32_e32 v128, v2
	v_mov_b32_e32 v129, v2
	v_mov_b32_e32 v154, v2
	v_mov_b32_e32 v155, v2
	v_mov_b32_e32 v156, v2
	v_mov_b32_e32 v157, v2
	v_mov_b32_e32 v158, v2
	v_mov_b32_e32 v159, v2
	v_mov_b32_e32 v160, v2
	v_mov_b32_e32 v161, v2
.LBB0_195:
	s_add_i32 vcc_lo, vcc_lo, 2
	ds_read_b128 v[58:61], v249
	ds_read_b128 v[62:65], v249 offset:1024
	ds_read_b128 v[70:73], v249 offset:2048
	ds_read_b128 v[74:77], v249 offset:3072
	s_add_i32 m0, s21, 0xc000
	ds_read_b128 v[138:141], v196
	ds_read_b128 v[142:145], v196 offset:1024
	ds_read_b128 v[146:149], v196 offset:2048
	ds_read_b128 v[150:153], v196 offset:3072
	ds_read_b128 v[162:165], v196 offset:4096
	ds_read_b128 v[166:169], v196 offset:5120
	ds_read_b128 v[170:173], v196 offset:6144
	global_load_lds_dwordx4 v0, s[100:101]
	s_add_i32 m0, s21, 0xe000
	ds_read_b128 v[184:187], v196 offset:7168
	global_load_lds_dwordx4 v174, s[100:101]
	s_waitcnt lgkmcnt(8)
	s_barrier
	s_waitcnt lgkmcnt(0)
	v_mfma_f32_16x16x32_bf16 v[158:161], v[58:61], v[138:141], v[158:161]
	v_mfma_f32_16x16x32_bf16 v[154:157], v[70:73], v[138:141], v[154:157]
	v_mfma_f32_16x16x32_bf16 v[126:129], v[58:61], v[146:149], v[126:129]
	v_mfma_f32_16x16x32_bf16 v[122:125], v[70:73], v[146:149], v[122:125]
	v_mfma_f32_16x16x32_bf16 v[110:113], v[58:61], v[162:165], v[110:113]
	v_mfma_f32_16x16x32_bf16 v[106:109], v[70:73], v[162:165], v[106:109]
	v_mfma_f32_16x16x32_bf16 v[94:97], v[58:61], v[170:173], v[94:97]
	v_mfma_f32_16x16x32_bf16 v[90:93], v[70:73], v[170:173], v[90:93]
	v_mfma_f32_16x16x32_bf16 v[158:161], v[62:65], v[142:145], v[158:161]
	v_mfma_f32_16x16x32_bf16 v[154:157], v[74:77], v[142:145], v[154:157]
	v_mfma_f32_16x16x32_bf16 v[126:129], v[62:65], v[150:153], v[126:129]
	v_mfma_f32_16x16x32_bf16 v[122:125], v[74:77], v[150:153], v[122:125]
	v_mfma_f32_16x16x32_bf16 v[110:113], v[62:65], v[166:169], v[110:113]
	v_mfma_f32_16x16x32_bf16 v[106:109], v[74:77], v[166:169], v[106:109]
	v_mfma_f32_16x16x32_bf16 v[94:97], v[62:65], v[184:187], v[94:97]
	v_mfma_f32_16x16x32_bf16 v[90:93], v[74:77], v[184:187], v[90:93]
	s_barrier
	ds_read_b128 v[188:191], v249 offset:16384
	ds_read_b128 v[220:223], v249 offset:17408
	ds_read_b128 v[224:227], v249 offset:18432
	ds_read_b128 v[228:231], v249 offset:19456
	s_add_i32 m0, s20, 0x10000
	s_nop 0
	global_load_lds_dwordx4 v0, s[52:53]
	s_add_i32 m0, s20, 0x12000
	s_nop 0
	global_load_lds_dwordx4 v174, s[52:53]
	s_barrier
; #define PG8_STAGE(bufoff, gbase, voff) do { _Pragma("unroll") for (int _i = 0; _i < 2; ++_i) \
;         __builtin_amdgcn_global_load_lds((const unsigned*)((const char*)(gbase) + (voff)[_i]), (LAS unsigned*)(lds + (bufoff) + ldsw + _i * 8192), 16, 0, 0); } while (0)
; #define PG8_LDA(dst, b, h) do { _Pragma("unroll") for (int m = 0; m < 4; ++m) _Pragma("unroll") for (int k = 0; k < 2; ++k) dst[m][k] = *(const LAS bf16x8*)(lds + PG8_SA(b, h) + aoff + m * 2048 + k * 1024); } while (0)
; #define PG8_LDB(dst, b, h) do { _Pragma("unroll") for (int n = 0; n < 2; ++n) _Pragma("unroll") for (int k = 0; k < 2; ++k) dst[n][k] = *(const LAS bf16x8*)(lds + PG8_SB(b, h) + boff + n * 2048 + k * 1024); } while (0)
; #define PG8_MMA(ai, bj, At, Bt) do { __builtin_amdgcn_s_setprio(1); _Pragma("unroll") for (int m = 0; m < 4; ++m) _Pragma("unroll") for (int n = 0; n < 2; ++n) _Pragma("unroll") for (int k = 0; k < 2; ++k) \
;         acc[ai][bj][m][n] = __builtin_amdgcn_mfma_f32_16x16x32_bf16(Bt[n][k], At[m][k], acc[ai][bj][m][n], 0, 0, 0); __builtin_amdgcn_s_setprio(0); } while (0)
; #define PG8_WAIT_V(n) asm volatile("s_waitcnt vmcnt(" #n ")" ::: "memory")
; #define PG8_WAIT_L(n) asm volatile("s_waitcnt lgkmcnt(" #n ")" ::: "memory")
; #define PG8_BAR __builtin_amdgcn_s_barrier()
; #define PG8_SCHED __builtin_amdgcn_sched_barrier(0)
; template <int MODE, class EpiT, class Sched>
; __device__ __forceinline__ void gemm_phase(LAS unsigned char* lds, const Gemm g, const Sched& S, const EpiT& E) {
;     ...
;             PG8_WAIT_L(8); PG8_BAR; PG8_WAIT_L(0); PG8_MMA(0, 0, At, B0); PG8_BAR; PG8_SCHED;
;             PG8_LDB(B1, 0, 1); PG8_STAGE(PG8_SB(0, 0), b2, voffB);
;             PG8_BAR; PG8_WAIT_L(0); PG8_MMA(0, 1, At, B1); PG8_BAR;
;             PG8_LDA(At, 0, 1); PG8_STAGE(PG8_SA(0, 0), a2, voffA);
;             PG8_BAR; PG8_WAIT_L(0); PG8_MMA(1, 0, At, B0); PG8_BAR; PG8_SCHED;
;             PG8_STAGE(PG8_SB(0, 1), b2 + hstep, voffB);
;             PG8_WAIT_V(6); PG8_BAR; PG8_MMA(1, 1, At, B1); PG8_BAR;
;             PG8_LDB(B0, 1, 0); PG8_SCHED; PG8_LDA(At, 1, 0); PG8_STAGE(PG8_SA(0, 1), a2 + hstep, voffA);
	s_waitcnt lgkmcnt(0)
	v_mfma_f32_16x16x32_bf16 v[134:137], v[188:191], v[138:141], v[134:137]
	v_mfma_f32_16x16x32_bf16 v[130:133], v[224:227], v[138:141], v[130:133]
	v_mfma_f32_16x16x32_bf16 v[118:121], v[188:191], v[146:149], v[118:121]
	v_mfma_f32_16x16x32_bf16 v[114:117], v[224:227], v[146:149], v[114:117]
	v_mfma_f32_16x16x32_bf16 v[102:105], v[188:191], v[162:165], v[102:105]
	v_mfma_f32_16x16x32_bf16 v[98:101], v[224:227], v[162:165], v[98:101]
	v_mfma_f32_16x16x32_bf16 v[86:89], v[188:191], v[170:173], v[86:89]
	v_mfma_f32_16x16x32_bf16 v[82:85], v[224:227], v[170:173], v[82:85]
	v_mfma_f32_16x16x32_bf16 v[134:137], v[220:223], v[142:145], v[134:137]
	v_mfma_f32_16x16x32_bf16 v[130:133], v[228:231], v[142:145], v[130:133]
	v_mfma_f32_16x16x32_bf16 v[118:121], v[220:223], v[150:153], v[118:121]
	v_mfma_f32_16x16x32_bf16 v[114:117], v[228:231], v[150:153], v[114:117]
	v_mfma_f32_16x16x32_bf16 v[102:105], v[220:223], v[166:169], v[102:105]
	v_mfma_f32_16x16x32_bf16 v[98:101], v[228:231], v[166:169], v[98:101]
	v_mfma_f32_16x16x32_bf16 v[86:89], v[220:223], v[184:187], v[86:89]
	v_mfma_f32_16x16x32_bf16 v[82:85], v[228:231], v[184:187], v[82:85]
	s_barrier
	s_mov_b32 m0, s21
	ds_read_b128 v[138:141], v196 offset:16384
	ds_read_b128 v[142:145], v196 offset:17408
	ds_read_b128 v[146:149], v196 offset:18432
	ds_read_b128 v[150:153], v196 offset:19456
	ds_read_b128 v[162:165], v196 offset:20480
	ds_read_b128 v[166:169], v196 offset:21504
	ds_read_b128 v[170:173], v196 offset:22528
	global_load_lds_dwordx4 v0, s[44:45]
	s_mov_b32 m0, s50
	ds_read_b128 v[184:187], v196 offset:23552
	global_load_lds_dwordx4 v174, s[44:45]
	s_barrier
	s_waitcnt lgkmcnt(0)
	v_mfma_f32_16x16x32_bf16 v[78:81], v[58:61], v[138:141], v[78:81]
	v_mfma_f32_16x16x32_bf16 v[66:69], v[70:73], v[138:141], v[66:69]
	v_mfma_f32_16x16x32_bf16 v[46:49], v[58:61], v[146:149], v[46:49]
	v_mfma_f32_16x16x32_bf16 v[42:45], v[70:73], v[146:149], v[42:45]
	v_mfma_f32_16x16x32_bf16 v[30:33], v[58:61], v[162:165], v[30:33]
	v_mfma_f32_16x16x32_bf16 v[26:29], v[70:73], v[162:165], v[26:29]
	v_mfma_f32_16x16x32_bf16 v[14:17], v[58:61], v[170:173], v[14:17]
	v_mfma_f32_16x16x32_bf16 v[10:13], v[70:73], v[170:173], v[10:13]
	v_mfma_f32_16x16x32_bf16 v[78:81], v[62:65], v[142:145], v[78:81]
	v_mfma_f32_16x16x32_bf16 v[66:69], v[74:77], v[142:145], v[66:69]
	v_mfma_f32_16x16x32_bf16 v[46:49], v[62:65], v[150:153], v[46:49]
	v_mfma_f32_16x16x32_bf16 v[42:45], v[74:77], v[150:153], v[42:45]
	v_mfma_f32_16x16x32_bf16 v[30:33], v[62:65], v[166:169], v[30:33]
	v_mfma_f32_16x16x32_bf16 v[26:29], v[74:77], v[166:169], v[26:29]
	v_mfma_f32_16x16x32_bf16 v[14:17], v[62:65], v[184:187], v[14:17]
	v_mfma_f32_16x16x32_bf16 v[10:13], v[74:77], v[184:187], v[10:13]
	s_barrier
	s_add_u32 s100, s44, 0x80
	s_addc_u32 s101, s45, 0
	s_add_u32 s44, s44, s38
	s_addc_u32 s45, s45, 0
	s_add_u32 s52, s52, s38
	s_addc_u32 s53, s53, 0
	s_add_i32 m0, s20, 0x14000
	s_nop 0
	global_load_lds_dwordx4 v0, s[52:53]
	s_add_i32 m0, s20, 0x16000
	s_nop 0
	global_load_lds_dwordx4 v174, s[52:53]
	s_add_u32 s4, s4, 0x100
	s_addc_u32 s5, s5, 0
	s_add_u32 s89, s89, 0x100
	s_addc_u32 s90, s90, 0
	s_waitcnt vmcnt(6)
	s_barrier
	v_mfma_f32_16x16x32_bf16 v[54:57], v[188:191], v[138:141], v[54:57]
	v_mfma_f32_16x16x32_bf16 v[50:53], v[224:227], v[138:141], v[50:53]
	v_mfma_f32_16x16x32_bf16 v[38:41], v[188:191], v[146:149], v[38:41]
	v_mfma_f32_16x16x32_bf16 v[34:37], v[224:227], v[146:149], v[34:37]
	v_mfma_f32_16x16x32_bf16 v[22:25], v[188:191], v[162:165], v[22:25]
	v_mfma_f32_16x16x32_bf16 v[18:21], v[224:227], v[162:165], v[18:21]
	v_mfma_f32_16x16x32_bf16 v[6:9], v[188:191], v[170:173], v[6:9]
	v_mfma_f32_16x16x32_bf16 v[2:5], v[224:227], v[170:173], v[2:5]
	v_mfma_f32_16x16x32_bf16 v[54:57], v[220:223], v[142:145], v[54:57]
	v_mfma_f32_16x16x32_bf16 v[50:53], v[228:231], v[142:145], v[50:53]
	v_mfma_f32_16x16x32_bf16 v[38:41], v[220:223], v[150:153], v[38:41]
	v_mfma_f32_16x16x32_bf16 v[34:37], v[228:231], v[150:153], v[34:37]
	v_mfma_f32_16x16x32_bf16 v[22:25], v[220:223], v[166:169], v[22:25]
	v_mfma_f32_16x16x32_bf16 v[18:21], v[228:231], v[166:169], v[18:21]
	v_mfma_f32_16x16x32_bf16 v[6:9], v[220:223], v[184:187], v[6:9]
	v_mfma_f32_16x16x32_bf16 v[2:5], v[228:231], v[184:187], v[2:5]
	s_barrier
	ds_read_b128 v[58:61], v249 offset:32768
	ds_read_b128 v[62:65], v249 offset:33792
	ds_read_b128 v[70:73], v249 offset:34816
	ds_read_b128 v[74:77], v249 offset:35840
	s_mov_b32 m0, s51
	ds_read_b128 v[138:141], v196 offset:32768
	ds_read_b128 v[142:145], v196 offset:33792
	ds_read_b128 v[146:149], v196 offset:34816
	ds_read_b128 v[150:153], v196 offset:35840
	ds_read_b128 v[162:165], v196 offset:36864
	ds_read_b128 v[166:169], v196 offset:37888
	ds_read_b128 v[170:173], v196 offset:38912
	global_load_lds_dwordx4 v0, s[44:45]
	s_mov_b32 m0, s56
	ds_read_b128 v[184:187], v196 offset:39936
	global_load_lds_dwordx4 v174, s[44:45]
	s_waitcnt lgkmcnt(8)
	s_barrier
	s_waitcnt lgkmcnt(0)
	v_mfma_f32_16x16x32_bf16 v[158:161], v[58:61], v[138:141], v[158:161]
	v_mfma_f32_16x16x32_bf16 v[154:157], v[70:73], v[138:141], v[154:157]
	v_mfma_f32_16x16x32_bf16 v[126:129], v[58:61], v[146:149], v[126:129]
	v_mfma_f32_16x16x32_bf16 v[122:125], v[70:73], v[146:149], v[122:125]
	v_mfma_f32_16x16x32_bf16 v[110:113], v[58:61], v[162:165], v[110:113]
	v_mfma_f32_16x16x32_bf16 v[106:109], v[70:73], v[162:165], v[106:109]
	v_mfma_f32_16x16x32_bf16 v[94:97], v[58:61], v[170:173], v[94:97]
	v_mfma_f32_16x16x32_bf16 v[90:93], v[70:73], v[170:173], v[90:93]
	v_mfma_f32_16x16x32_bf16 v[158:161], v[62:65], v[142:145], v[158:161]
	v_mfma_f32_16x16x32_bf16 v[154:157], v[74:77], v[142:145], v[154:157]
	v_mfma_f32_16x16x32_bf16 v[126:129], v[62:65], v[150:153], v[126:129]
	v_mfma_f32_16x16x32_bf16 v[122:125], v[74:77], v[150:153], v[122:125]
	v_mfma_f32_16x16x32_bf16 v[110:113], v[62:65], v[166:169], v[110:113]
	v_mfma_f32_16x16x32_bf16 v[106:109], v[74:77], v[166:169], v[106:109]
	v_mfma_f32_16x16x32_bf16 v[94:97], v[62:65], v[184:187], v[94:97]
	v_mfma_f32_16x16x32_bf16 v[90:93], v[74:77], v[184:187], v[90:93]
	s_barrier
; #define PG8_STAGE(bufoff, gbase, voff) do { _Pragma("unroll") for (int _i = 0; _i < 2; ++_i) \
;         __builtin_amdgcn_global_load_lds((const unsigned*)((const char*)(gbase) + (voff)[_i]), (LAS unsigned*)(lds + (bufoff) + ldsw + _i * 8192), 16, 0, 0); } while (0)
; #define PG8_LDA(dst, b, h) do { _Pragma("unroll") for (int m = 0; m < 4; ++m) _Pragma("unroll") for (int k = 0; k < 2; ++k) dst[m][k] = *(const LAS bf16x8*)(lds + PG8_SA(b, h) + aoff + m * 2048 + k * 1024); } while (0)
; #define PG8_LDB(dst, b, h) do { _Pragma("unroll") for (int n = 0; n < 2; ++n) _Pragma("unroll") for (int k = 0; k < 2; ++k) dst[n][k] = *(const LAS bf16x8*)(lds + PG8_SB(b, h) + boff + n * 2048 + k * 1024); } while (0)
; #define PG8_MMA(ai, bj, At, Bt) do { __builtin_amdgcn_s_setprio(1); _Pragma("unroll") for (int m = 0; m < 4; ++m) _Pragma("unroll") for (int n = 0; n < 2; ++n) _Pragma("unroll") for (int k = 0; k < 2; ++k) \
;         acc[ai][bj][m][n] = __builtin_amdgcn_mfma_f32_16x16x32_bf16(Bt[n][k], At[m][k], acc[ai][bj][m][n], 0, 0, 0); __builtin_amdgcn_s_setprio(0); } while (0)
; #define PG8_WAIT_V(n) asm volatile("s_waitcnt vmcnt(" #n ")" ::: "memory")
;     template <int mode> __device__ __forceinline__ void run(const f32x4 (&acc)[2][2][4][2], const Unit& u, int wr, int wc, int fr, int fq, const LAS float* sc) const {
;     ...
;             const int col0 = u.pn * BM + wc * 32 + 8 * fq;
;             float sA = 1.f, sB = 1.f;
;             if (mode == 4) scales2(u, wr, fr, fq, sA, sB);
;             f32x4 bvv[4];
; #pragma unroll
;             for (int q = 0; q < 4; ++q) bvv[q] = (mode != 4 && bias) ? *(const f32x4*)(bias + col0 + (q >> 1) * HALF + (q & 1) * 4) : (f32x4){0.f, 0.f, 0.f, 0.f};
; template <int MODE, class EpiT, class Sched>
; __device__ __forceinline__ void gemm_phase(LAS unsigned char* lds, const Gemm g, const Sched& S, const EpiT& E) {
;     ...
;             PG8_WAIT_L(8); PG8_BAR; PG8_WAIT_L(0); PG8_MMA(0, 0, At, B0); PG8_BAR; PG8_SCHED;
;             PG8_LDB(B1, 1, 1); PG8_STAGE(PG8_SB(1, 0), b3, voffB);
;             PG8_BAR; PG8_WAIT_L(0); PG8_MMA(0, 1, At, B1); PG8_BAR;
;             PG8_LDA(At, 1, 1); PG8_STAGE(PG8_SA(1, 0), a3, voffA);
;             PG8_BAR; PG8_WAIT_L(0); PG8_MMA(1, 0, At, B0); PG8_BAR; PG8_SCHED;
;             PG8_STAGE(PG8_SB(1, 1), b3 + hstep, voffB);
;             PG8_WAIT_V(6); PG8_BAR; PG8_MMA(1, 1, At, B1); PG8_BAR;
	s_add_i32 m0, s20, 0x18000
	ds_read_b128 v[188:191], v249 offset:49152
	ds_read_b128 v[220:223], v249 offset:50176
	ds_read_b128 v[224:227], v249 offset:51200
	global_load_lds_dwordx4 v0, s[98:99]
	s_add_i32 m0, s20, 0x1a000
	ds_read_b128 v[228:231], v249 offset:52224
	global_load_lds_dwordx4 v174, s[98:99]
	s_barrier
	s_waitcnt lgkmcnt(0)
	v_mfma_f32_16x16x32_bf16 v[134:137], v[188:191], v[138:141], v[134:137]
	v_mfma_f32_16x16x32_bf16 v[130:133], v[224:227], v[138:141], v[130:133]
	v_mfma_f32_16x16x32_bf16 v[118:121], v[188:191], v[146:149], v[118:121]
	v_mfma_f32_16x16x32_bf16 v[114:117], v[224:227], v[146:149], v[114:117]
	v_mfma_f32_16x16x32_bf16 v[102:105], v[188:191], v[162:165], v[102:105]
	v_mfma_f32_16x16x32_bf16 v[98:101], v[224:227], v[162:165], v[98:101]
	v_mfma_f32_16x16x32_bf16 v[86:89], v[188:191], v[170:173], v[86:89]
	v_mfma_f32_16x16x32_bf16 v[82:85], v[224:227], v[170:173], v[82:85]
	v_mfma_f32_16x16x32_bf16 v[134:137], v[220:223], v[142:145], v[134:137]
	v_mfma_f32_16x16x32_bf16 v[130:133], v[228:231], v[142:145], v[130:133]
	v_mfma_f32_16x16x32_bf16 v[118:121], v[220:223], v[150:153], v[118:121]
	v_mfma_f32_16x16x32_bf16 v[114:117], v[228:231], v[150:153], v[114:117]
	v_mfma_f32_16x16x32_bf16 v[102:105], v[220:223], v[166:169], v[102:105]
	v_mfma_f32_16x16x32_bf16 v[98:101], v[228:231], v[166:169], v[98:101]
	v_mfma_f32_16x16x32_bf16 v[86:89], v[220:223], v[184:187], v[86:89]
	v_mfma_f32_16x16x32_bf16 v[82:85], v[228:231], v[184:187], v[82:85]
	s_barrier
	s_mov_b32 m0, s61
	ds_read_b128 v[138:141], v196 offset:49152
	ds_read_b128 v[142:145], v196 offset:50176
	ds_read_b128 v[146:149], v196 offset:51200
	ds_read_b128 v[150:153], v196 offset:52224
	ds_read_b128 v[162:165], v196 offset:53248
	ds_read_b128 v[166:169], v196 offset:54272
	ds_read_b128 v[170:173], v196 offset:55296
	global_load_lds_dwordx4 v0, s[100:101]
	s_mov_b32 m0, s74
	ds_read_b128 v[184:187], v196 offset:56320
	global_load_lds_dwordx4 v174, s[100:101]
	s_barrier
	s_waitcnt lgkmcnt(0)
	v_mfma_f32_16x16x32_bf16 v[78:81], v[58:61], v[138:141], v[78:81]
	v_mfma_f32_16x16x32_bf16 v[66:69], v[70:73], v[138:141], v[66:69]
	v_mfma_f32_16x16x32_bf16 v[46:49], v[58:61], v[146:149], v[46:49]
	v_mfma_f32_16x16x32_bf16 v[42:45], v[70:73], v[146:149], v[42:45]
	v_mfma_f32_16x16x32_bf16 v[30:33], v[58:61], v[162:165], v[30:33]
	v_mfma_f32_16x16x32_bf16 v[26:29], v[70:73], v[162:165], v[26:29]
	v_mfma_f32_16x16x32_bf16 v[14:17], v[58:61], v[170:173], v[14:17]
	v_mfma_f32_16x16x32_bf16 v[10:13], v[70:73], v[170:173], v[10:13]
	v_mfma_f32_16x16x32_bf16 v[78:81], v[62:65], v[142:145], v[78:81]
	v_mfma_f32_16x16x32_bf16 v[66:69], v[74:77], v[142:145], v[66:69]
	v_mfma_f32_16x16x32_bf16 v[46:49], v[62:65], v[150:153], v[46:49]
	v_mfma_f32_16x16x32_bf16 v[42:45], v[74:77], v[150:153], v[42:45]
	v_mfma_f32_16x16x32_bf16 v[30:33], v[62:65], v[166:169], v[30:33]
	v_mfma_f32_16x16x32_bf16 v[26:29], v[74:77], v[166:169], v[26:29]
	v_mfma_f32_16x16x32_bf16 v[14:17], v[62:65], v[184:187], v[14:17]
	v_mfma_f32_16x16x32_bf16 v[10:13], v[74:77], v[184:187], v[10:13]
	s_barrier
	s_add_u32 s98, s98, s38
	s_addc_u32 s99, s99, 0
	s_add_i32 m0, s20, 0x1c000
	s_nop 0
	global_load_lds_dwordx4 v0, s[98:99]
	s_add_i32 m0, s20, 0x1e000
	s_nop 0
	global_load_lds_dwordx4 v174, s[98:99]
	s_add_u32 s100, s4, 0x80
	s_addc_u32 s101, s5, 0
	s_cmp_eq_u32 s75, vcc_lo
	s_cselect_b32 s44, s68, s100
	s_cselect_b32 s45, s69, s101
	s_cselect_b32 s53, s47, s90
	s_cselect_b32 s52, s46, s89
	s_add_u32 s98, s52, 0x80
	s_addc_u32 s99, s53, 0
	s_add_u32 s100, s4, s38
	s_addc_u32 s101, s5, 0
	s_waitcnt vmcnt(6)
	s_barrier
	v_mfma_f32_16x16x32_bf16 v[54:57], v[188:191], v[138:141], v[54:57]
	v_mfma_f32_16x16x32_bf16 v[50:53], v[224:227], v[138:141], v[50:53]
	v_mfma_f32_16x16x32_bf16 v[38:41], v[188:191], v[146:149], v[38:41]
	v_mfma_f32_16x16x32_bf16 v[34:37], v[224:227], v[146:149], v[34:37]
	v_mfma_f32_16x16x32_bf16 v[22:25], v[188:191], v[162:165], v[22:25]
	v_mfma_f32_16x16x32_bf16 v[18:21], v[224:227], v[162:165], v[18:21]
	v_mfma_f32_16x16x32_bf16 v[6:9], v[188:191], v[170:173], v[6:9]
	v_mfma_f32_16x16x32_bf16 v[2:5], v[224:227], v[170:173], v[2:5]
	v_mfma_f32_16x16x32_bf16 v[54:57], v[220:223], v[142:145], v[54:57]
	v_mfma_f32_16x16x32_bf16 v[50:53], v[228:231], v[142:145], v[50:53]
	v_mfma_f32_16x16x32_bf16 v[38:41], v[220:223], v[150:153], v[38:41]
	v_mfma_f32_16x16x32_bf16 v[34:37], v[228:231], v[150:153], v[34:37]
	v_mfma_f32_16x16x32_bf16 v[22:25], v[220:223], v[166:169], v[22:25]
	v_mfma_f32_16x16x32_bf16 v[18:21], v[228:231], v[166:169], v[18:21]
	v_mfma_f32_16x16x32_bf16 v[6:9], v[220:223], v[184:187], v[6:9]
	v_mfma_f32_16x16x32_bf16 v[2:5], v[228:231], v[184:187], v[2:5]
	s_barrier
	s_cmp_ge_u32 vcc_lo, s60
	s_cbranch_scc0 .LBB0_195
	v_lshl_or_b32 v186, s24, 8, v195
	v_ashrrev_i32_e32 v187, 31, v186
	v_mov_b32_e32 v70, 0
	v_cndmask_b32_e64 v58, 0, 1, s[78:79]
	v_lshl_add_u64 v[138:139], v[186:187], 2, s[12:13]
	v_cmp_ne_u32_e64 s[44:45], 1, v58
	s_andn2_b64 vcc, exec, s[78:79]
	v_mov_b32_e32 v74, 0
	v_mov_b32_e32 v75, v70
	v_mov_b32_e32 v184, 0
	v_mov_b32_e32 v185, v70
	s_cbranch_vccnz .LBB0_198
	global_load_dwordx4 v[74:77], v[138:139], off
	s_waitcnt vmcnt(0)
	v_mov_b32_e32 v184, v76
	v_mov_b32_e32 v185, v77
